# instruction selection: in-proj GEMM accumulators cleared with 64 v_mov_b64 instead of 128 v_mov_b32 per unit
# baseline (speedup 1.0000x reference)
; template <class Epi, class Sched>
; __device__ __forceinline__ void gemm_phase(const int TID, LAS unsigned char* lds, const int lda, const int ldb, const Sched& S, const Epi& E) {
;     ...
; #pragma unroll
;         for (int a = 0; a < 2; ++a)
; #pragma unroll
;             for (int b = 0; b < 2; ++b)
; #pragma unroll
;                 for (int m = 0; m < 4; ++m)
; #pragma unroll
;                     for (int n = 0; n < 2; ++n) acc[a][b][m][n] = (f32x4){0.f, 0.f, 0.f, 0.f};
;         cur = nxt; cA = nA; cB = nB; ++ui;
.LBB0_1227:
	s_add_u32 s3, s48, 0x100
	s_addc_u32 s24, s49, 0
	s_add_u32 s46, s46, 0x80080
	s_addc_u32 s47, s47, 0
	s_mov_b32 s29, -2
	s_waitcnt lgkmcnt(0)
	v_mov_b64_e32 v[0:1], 0
	v_mov_b64_e32 v[2:3], 0
	v_mov_b64_e32 v[4:5], 0
	v_mov_b64_e32 v[6:7], 0
	v_mov_b64_e32 v[8:9], 0
	v_mov_b64_e32 v[10:11], 0
	v_mov_b64_e32 v[18:19], 0
	v_mov_b64_e32 v[20:21], 0
	v_mov_b64_e32 v[22:23], 0
	v_mov_b64_e32 v[24:25], 0
	v_mov_b64_e32 v[26:27], 0
	v_mov_b64_e32 v[28:29], 0
	v_mov_b64_e32 v[30:31], 0
	v_mov_b64_e32 v[32:33], 0
	v_mov_b64_e32 v[34:35], 0
	v_mov_b64_e32 v[36:37], 0
	v_mov_b64_e32 v[38:39], 0
	v_mov_b64_e32 v[40:41], 0
	v_mov_b64_e32 v[42:43], 0
	v_mov_b64_e32 v[44:45], 0
	v_mov_b64_e32 v[46:47], 0
	v_mov_b64_e32 v[48:49], 0
	v_mov_b64_e32 v[50:51], 0
	v_mov_b64_e32 v[52:53], 0
	v_mov_b64_e32 v[54:55], 0
	v_mov_b64_e32 v[56:57], 0
	v_mov_b64_e32 v[58:59], 0
	v_mov_b64_e32 v[60:61], 0
	v_mov_b64_e32 v[62:63], 0
	v_mov_b64_e32 v[64:65], 0
	v_mov_b64_e32 v[66:67], 0
	v_mov_b64_e32 v[68:69], 0
	v_mov_b64_e32 v[70:71], 0
	v_mov_b64_e32 v[72:73], 0
	v_mov_b64_e32 v[74:75], 0
	v_mov_b64_e32 v[76:77], 0
	v_mov_b64_e32 v[78:79], 0
	v_mov_b64_e32 v[80:81], 0
	v_mov_b64_e32 v[82:83], 0
	v_mov_b64_e32 v[84:85], 0
	v_mov_b64_e32 v[86:87], 0
	v_mov_b64_e32 v[88:89], 0
	v_mov_b64_e32 v[90:91], 0
	v_mov_b64_e32 v[92:93], 0
	v_mov_b64_e32 v[94:95], 0
	v_mov_b64_e32 v[96:97], 0
	v_mov_b64_e32 v[98:99], 0
	v_mov_b64_e32 v[100:101], 0
	v_mov_b64_e32 v[102:103], 0
	v_mov_b64_e32 v[104:105], 0
	v_mov_b64_e32 v[106:107], 0
	v_mov_b64_e32 v[108:109], 0
	v_mov_b64_e32 v[110:111], 0
	v_mov_b64_e32 v[112:113], 0
	v_mov_b64_e32 v[114:115], 0
	v_mov_b64_e32 v[116:117], 0
	v_mov_b64_e32 v[118:119], 0
	v_mov_b64_e32 v[120:121], 0
	v_mov_b64_e32 v[122:123], 0
	v_mov_b64_e32 v[124:125], 0
	v_mov_b64_e32 v[126:127], 0
	v_mov_b64_e32 v[128:129], 0
	v_mov_b64_e32 v[130:131], 0
	v_mov_b64_e32 v[132:133], 0
